# prep: mLSTM half uses jp^128 (rebalance 10->9 max jobs); GLA decay-gate loop reads weights with ds_read_b128 (4 k per block), two log-sigmoid chains interleaved
# speedup vs baseline: 1.0067x; 1.0067x over previous
.LBB0_593:
	ds_read_b128 v[196:199], v83 offset:3072
	ds_read_b128 v[234:237], v83 offset:0
	ds_read_b128 v[238:241], v83 offset:192
	ds_read_b128 v[242:245], v83 offset:384
	ds_read_b128 v[246:249], v83 offset:576
	ds_read_b128 v[250:253], v83 offset:768
	ds_read_b128 v[192:195], v83 offset:960
	ds_read_b128 v[200:203], v83 offset:1152
	ds_read_b128 v[86:89], v83 offset:1344
	s_waitcnt lgkmcnt(4)
	v_fmac_f32_e32 v196, v234, v77
	v_fmac_f32_e32 v197, v235, v77
	v_fmac_f32_e32 v198, v236, v77
	v_fmac_f32_e32 v199, v237, v77
	v_fmac_f32_e32 v196, v238, v78
	v_fmac_f32_e32 v197, v239, v78
	v_fmac_f32_e32 v198, v240, v78
	v_fmac_f32_e32 v199, v241, v78
	v_fmac_f32_e32 v196, v242, v79
	v_fmac_f32_e32 v197, v243, v79
	v_fmac_f32_e32 v198, v244, v79
	v_fmac_f32_e32 v199, v245, v79
	v_fmac_f32_e32 v196, v246, v80
	v_fmac_f32_e32 v197, v247, v80
	v_fmac_f32_e32 v198, v248, v80
	v_fmac_f32_e32 v199, v249, v80
	ds_read_b128 v[234:237], v83 offset:1536
	ds_read_b128 v[238:241], v83 offset:1728
	ds_read_b128 v[242:245], v83 offset:1920
	ds_read_b128 v[246:249], v83 offset:2112
	s_waitcnt lgkmcnt(4)
	v_fmac_f32_e32 v196, v250, v81
	v_fmac_f32_e32 v197, v251, v81
	v_fmac_f32_e32 v198, v252, v81
	v_fmac_f32_e32 v199, v253, v81
	v_fmac_f32_e32 v196, v192, v82
	v_fmac_f32_e32 v197, v193, v82
	v_fmac_f32_e32 v198, v194, v82
	v_fmac_f32_e32 v199, v195, v82
	v_pk_mul_f32 v[90:91], v[200:201], v[2:3] op_sel_hi:[1,0]
	v_pk_mul_f32 v[204:205], v[202:203], v[2:3] op_sel_hi:[1,0]
	v_add_f32_e32 v196, v196, v90
	v_add_f32_e32 v197, v197, v91
	v_add_f32_e32 v198, v198, v204
	v_add_f32_e32 v199, v199, v205
	v_pk_mul_f32 v[90:91], v[86:87], v[2:3] op_sel:[0,1] op_sel_hi:[1,1]
	v_pk_mul_f32 v[204:205], v[88:89], v[2:3] op_sel:[0,1] op_sel_hi:[1,1]
	v_add_f32_e32 v196, v196, v90
	v_add_f32_e32 v197, v197, v91
	v_add_f32_e32 v198, v198, v204
	v_add_f32_e32 v199, v199, v205
	ds_read_b128 v[250:253], v83 offset:2304
	ds_read_b128 v[192:195], v83 offset:2496
	ds_read_b128 v[200:203], v83 offset:2688
	ds_read_b128 v[86:89], v83 offset:2880
	s_waitcnt lgkmcnt(4)
	v_pk_mul_f32 v[90:91], v[234:235], v[68:69] op_sel_hi:[1,0]
	v_pk_mul_f32 v[204:205], v[236:237], v[68:69] op_sel_hi:[1,0]
	v_add_f32_e32 v196, v196, v90
	v_add_f32_e32 v197, v197, v91
	v_add_f32_e32 v198, v198, v204
	v_add_f32_e32 v199, v199, v205
	v_pk_mul_f32 v[90:91], v[238:239], v[68:69] op_sel:[0,1] op_sel_hi:[1,1]
	v_pk_mul_f32 v[204:205], v[240:241], v[68:69] op_sel:[0,1] op_sel_hi:[1,1]
	v_add_f32_e32 v196, v196, v90
	v_add_f32_e32 v197, v197, v91
	v_add_f32_e32 v198, v198, v204
	v_add_f32_e32 v199, v199, v205
	v_pk_mul_f32 v[90:91], v[242:243], v[70:71] op_sel_hi:[1,0]
	v_pk_mul_f32 v[204:205], v[244:245], v[70:71] op_sel_hi:[1,0]
	v_add_f32_e32 v196, v196, v90
	v_add_f32_e32 v197, v197, v91
	v_add_f32_e32 v198, v198, v204
	v_add_f32_e32 v199, v199, v205
	v_pk_mul_f32 v[90:91], v[246:247], v[70:71] op_sel:[0,1] op_sel_hi:[1,1]
	v_pk_mul_f32 v[204:205], v[248:249], v[70:71] op_sel:[0,1] op_sel_hi:[1,1]
	v_add_f32_e32 v196, v196, v90
	v_add_f32_e32 v197, v197, v91
	v_add_f32_e32 v198, v198, v204
	v_add_f32_e32 v199, v199, v205
	s_waitcnt lgkmcnt(0)
	v_pk_mul_f32 v[90:91], v[250:251], v[72:73] op_sel_hi:[1,0]
	v_pk_mul_f32 v[204:205], v[252:253], v[72:73] op_sel_hi:[1,0]
	v_add_f32_e32 v196, v196, v90
	v_add_f32_e32 v197, v197, v91
	v_add_f32_e32 v198, v198, v204
	v_add_f32_e32 v199, v199, v205
	v_pk_mul_f32 v[90:91], v[192:193], v[72:73] op_sel:[0,1] op_sel_hi:[1,1]
	v_pk_mul_f32 v[204:205], v[194:195], v[72:73] op_sel:[0,1] op_sel_hi:[1,1]
	v_add_f32_e32 v196, v196, v90
	v_add_f32_e32 v197, v197, v91
	v_add_f32_e32 v198, v198, v204
	v_add_f32_e32 v199, v199, v205
	v_pk_mul_f32 v[90:91], v[200:201], v[74:75] op_sel_hi:[1,0]
	v_pk_mul_f32 v[204:205], v[202:203], v[74:75] op_sel_hi:[1,0]
	v_add_f32_e32 v196, v196, v90
	v_add_f32_e32 v197, v197, v91
	v_add_f32_e32 v198, v198, v204
	v_add_f32_e32 v199, v199, v205
	v_pk_mul_f32 v[90:91], v[86:87], v[74:75] op_sel:[0,1] op_sel_hi:[1,1]
	v_pk_mul_f32 v[204:205], v[88:89], v[74:75] op_sel:[0,1] op_sel_hi:[1,1]
	v_add_f32_e32 v196, v196, v90
	v_add_f32_e32 v197, v197, v91
	v_add_f32_e32 v198, v198, v204
	v_add_f32_e32 v199, v199, v205
	v_min_f32_e32 v85, 0, v196
	v_min_f32_e32 v191, 0, v197
	v_mul_f32_e64 v196, |v196|, s36
	v_mul_f32_e64 v197, |v197|, s36
	v_exp_f32_e32 v196, v196
	v_exp_f32_e32 v197, v197
	s_nop 0
	v_add_f32_e32 v196, 1.0, v196
	v_add_f32_e32 v197, 1.0, v197
	v_cmp_gt_f32_e32 vcc, s5, v196
	v_cmp_gt_f32_e64 s[38:39], s5, v197
	s_nop 1
	v_cndmask_b32_e64 v107, 0, 32, vcc
	v_cndmask_b32_e64 v233, 0, 32, s[38:39]
	v_ldexp_f32 v196, v196, v107
	v_ldexp_f32 v197, v197, v233
	v_log_f32_e32 v196, v196
	v_log_f32_e32 v197, v197
	v_cndmask_b32_e32 v107, 0, v223, vcc
	v_cndmask_b32_e64 v233, 0, v223, s[38:39]
	v_mul_f32_e32 v121, 0x3f317217, v196
	v_mul_f32_e32 v205, 0x3f317217, v197
	v_fma_f32 v121, v196, s75, -v121
	v_fma_f32 v205, v197, s75, -v205
	v_fmac_f32_e32 v121, 0x3377d1cf, v196
	v_fmac_f32_e32 v205, 0x3377d1cf, v197
	v_fmac_f32_e32 v121, 0x3f317217, v196
	v_fmac_f32_e32 v205, 0x3f317217, v197
	v_cmp_lt_f32_e64 vcc, |v196|, s33
	v_cmp_lt_f32_e64 s[38:39], |v197|, s33
	s_nop 1
	v_cndmask_b32_e32 v196, v196, v121, vcc
	v_cndmask_b32_e64 v197, v197, v205, s[38:39]
	v_sub_f32_e32 v196, v196, v107
	v_sub_f32_e32 v197, v197, v233
	v_sub_f32_e32 v196, v85, v196
	v_sub_f32_e32 v197, v191, v197
	v_mul_f32_e32 v196, 0x3d800000, v196
	v_mul_f32_e32 v197, 0x3d800000, v197
	ds_write_b32 v84, v196
	ds_write_b32 v84, v197 offset:4
	v_min_f32_e32 v85, 0, v198
	v_min_f32_e32 v191, 0, v199
	v_mul_f32_e64 v198, |v198|, s36
	v_mul_f32_e64 v199, |v199|, s36
	v_exp_f32_e32 v198, v198
	v_exp_f32_e32 v199, v199
	s_nop 0
	v_add_f32_e32 v198, 1.0, v198
	v_add_f32_e32 v199, 1.0, v199
	v_cmp_gt_f32_e32 vcc, s5, v198
	v_cmp_gt_f32_e64 s[38:39], s5, v199
	s_nop 1
	v_cndmask_b32_e64 v107, 0, 32, vcc
	v_cndmask_b32_e64 v233, 0, 32, s[38:39]
	v_ldexp_f32 v198, v198, v107
	v_ldexp_f32 v199, v199, v233
	v_log_f32_e32 v198, v198
	v_log_f32_e32 v199, v199
	v_cndmask_b32_e32 v107, 0, v223, vcc
	v_cndmask_b32_e64 v233, 0, v223, s[38:39]
	v_mul_f32_e32 v121, 0x3f317217, v198
	v_mul_f32_e32 v205, 0x3f317217, v199
	v_fma_f32 v121, v198, s75, -v121
	v_fma_f32 v205, v199, s75, -v205
	v_fmac_f32_e32 v121, 0x3377d1cf, v198
	v_fmac_f32_e32 v205, 0x3377d1cf, v199
	v_fmac_f32_e32 v121, 0x3f317217, v198
	v_fmac_f32_e32 v205, 0x3f317217, v199
	v_cmp_lt_f32_e64 vcc, |v198|, s33
	v_cmp_lt_f32_e64 s[38:39], |v199|, s33
	s_nop 1
	v_cndmask_b32_e32 v198, v198, v121, vcc
	v_cndmask_b32_e64 v199, v199, v205, s[38:39]
	v_sub_f32_e32 v198, v198, v107
	v_sub_f32_e32 v199, v199, v233
	v_sub_f32_e32 v198, v85, v198
	v_sub_f32_e32 v199, v191, v199
	v_mul_f32_e32 v198, 0x3d800000, v198
	v_mul_f32_e32 v199, 0x3d800000, v199
	ds_write_b32 v84, v198 offset:8
	ds_write_b32 v84, v199 offset:12
	ds_read_b128 v[196:199], v83 offset:3088
	ds_read_b128 v[234:237], v83 offset:16
	ds_read_b128 v[238:241], v83 offset:208
	ds_read_b128 v[242:245], v83 offset:400
	ds_read_b128 v[246:249], v83 offset:592
	ds_read_b128 v[250:253], v83 offset:784
	ds_read_b128 v[192:195], v83 offset:976
	ds_read_b128 v[200:203], v83 offset:1168
	ds_read_b128 v[86:89], v83 offset:1360
	s_waitcnt lgkmcnt(4)
	v_fmac_f32_e32 v196, v234, v77
	v_fmac_f32_e32 v197, v235, v77
	v_fmac_f32_e32 v198, v236, v77
	v_fmac_f32_e32 v199, v237, v77
	v_fmac_f32_e32 v196, v238, v78
	v_fmac_f32_e32 v197, v239, v78
	v_fmac_f32_e32 v198, v240, v78
	v_fmac_f32_e32 v199, v241, v78
	v_fmac_f32_e32 v196, v242, v79
	v_fmac_f32_e32 v197, v243, v79
	v_fmac_f32_e32 v198, v244, v79
	v_fmac_f32_e32 v199, v245, v79
	v_fmac_f32_e32 v196, v246, v80
	v_fmac_f32_e32 v197, v247, v80
	v_fmac_f32_e32 v198, v248, v80
	v_fmac_f32_e32 v199, v249, v80
	ds_read_b128 v[234:237], v83 offset:1552
	ds_read_b128 v[238:241], v83 offset:1744
	ds_read_b128 v[242:245], v83 offset:1936
	ds_read_b128 v[246:249], v83 offset:2128
	s_waitcnt lgkmcnt(4)
	v_fmac_f32_e32 v196, v250, v81
	v_fmac_f32_e32 v197, v251, v81
	v_fmac_f32_e32 v198, v252, v81
	v_fmac_f32_e32 v199, v253, v81
	v_fmac_f32_e32 v196, v192, v82
	v_fmac_f32_e32 v197, v193, v82
	v_fmac_f32_e32 v198, v194, v82
	v_fmac_f32_e32 v199, v195, v82
	v_pk_mul_f32 v[90:91], v[200:201], v[2:3] op_sel_hi:[1,0]
	v_pk_mul_f32 v[204:205], v[202:203], v[2:3] op_sel_hi:[1,0]
	v_add_f32_e32 v196, v196, v90
	v_add_f32_e32 v197, v197, v91
	v_add_f32_e32 v198, v198, v204
	v_add_f32_e32 v199, v199, v205
	v_pk_mul_f32 v[90:91], v[86:87], v[2:3] op_sel:[0,1] op_sel_hi:[1,1]
	v_pk_mul_f32 v[204:205], v[88:89], v[2:3] op_sel:[0,1] op_sel_hi:[1,1]
	v_add_f32_e32 v196, v196, v90
	v_add_f32_e32 v197, v197, v91
	v_add_f32_e32 v198, v198, v204
	v_add_f32_e32 v199, v199, v205
	ds_read_b128 v[250:253], v83 offset:2320
	ds_read_b128 v[192:195], v83 offset:2512
	ds_read_b128 v[200:203], v83 offset:2704
	ds_read_b128 v[86:89], v83 offset:2896
	s_waitcnt lgkmcnt(4)
	v_pk_mul_f32 v[90:91], v[234:235], v[68:69] op_sel_hi:[1,0]
	v_pk_mul_f32 v[204:205], v[236:237], v[68:69] op_sel_hi:[1,0]
	v_add_f32_e32 v196, v196, v90
	v_add_f32_e32 v197, v197, v91
	v_add_f32_e32 v198, v198, v204
	v_add_f32_e32 v199, v199, v205
	v_pk_mul_f32 v[90:91], v[238:239], v[68:69] op_sel:[0,1] op_sel_hi:[1,1]
	v_pk_mul_f32 v[204:205], v[240:241], v[68:69] op_sel:[0,1] op_sel_hi:[1,1]
	v_add_f32_e32 v196, v196, v90
	v_add_f32_e32 v197, v197, v91
	v_add_f32_e32 v198, v198, v204
	v_add_f32_e32 v199, v199, v205
	v_pk_mul_f32 v[90:91], v[242:243], v[70:71] op_sel_hi:[1,0]
	v_pk_mul_f32 v[204:205], v[244:245], v[70:71] op_sel_hi:[1,0]
	v_add_f32_e32 v196, v196, v90
	v_add_f32_e32 v197, v197, v91
	v_add_f32_e32 v198, v198, v204
	v_add_f32_e32 v199, v199, v205
	v_pk_mul_f32 v[90:91], v[246:247], v[70:71] op_sel:[0,1] op_sel_hi:[1,1]
	v_pk_mul_f32 v[204:205], v[248:249], v[70:71] op_sel:[0,1] op_sel_hi:[1,1]
	v_add_f32_e32 v196, v196, v90
	v_add_f32_e32 v197, v197, v91
	v_add_f32_e32 v198, v198, v204
	v_add_f32_e32 v199, v199, v205
	s_waitcnt lgkmcnt(0)
	v_pk_mul_f32 v[90:91], v[250:251], v[72:73] op_sel_hi:[1,0]
	v_pk_mul_f32 v[204:205], v[252:253], v[72:73] op_sel_hi:[1,0]
	v_add_f32_e32 v196, v196, v90
	v_add_f32_e32 v197, v197, v91
	v_add_f32_e32 v198, v198, v204
	v_add_f32_e32 v199, v199, v205
	v_pk_mul_f32 v[90:91], v[192:193], v[72:73] op_sel:[0,1] op_sel_hi:[1,1]
	v_pk_mul_f32 v[204:205], v[194:195], v[72:73] op_sel:[0,1] op_sel_hi:[1,1]
	v_add_f32_e32 v196, v196, v90
	v_add_f32_e32 v197, v197, v91
	v_add_f32_e32 v198, v198, v204
	v_add_f32_e32 v199, v199, v205
	v_pk_mul_f32 v[90:91], v[200:201], v[74:75] op_sel_hi:[1,0]
	v_pk_mul_f32 v[204:205], v[202:203], v[74:75] op_sel_hi:[1,0]
	v_add_f32_e32 v196, v196, v90
	v_add_f32_e32 v197, v197, v91
	v_add_f32_e32 v198, v198, v204
	v_add_f32_e32 v199, v199, v205
	v_pk_mul_f32 v[90:91], v[86:87], v[74:75] op_sel:[0,1] op_sel_hi:[1,1]
	v_pk_mul_f32 v[204:205], v[88:89], v[74:75] op_sel:[0,1] op_sel_hi:[1,1]
	v_add_f32_e32 v196, v196, v90
	v_add_f32_e32 v197, v197, v91
	v_add_f32_e32 v198, v198, v204
	v_add_f32_e32 v199, v199, v205
	v_min_f32_e32 v85, 0, v196
	v_min_f32_e32 v191, 0, v197
	v_mul_f32_e64 v196, |v196|, s36
	v_mul_f32_e64 v197, |v197|, s36
	v_exp_f32_e32 v196, v196
	v_exp_f32_e32 v197, v197
	s_nop 0
	v_add_f32_e32 v196, 1.0, v196
	v_add_f32_e32 v197, 1.0, v197
	v_cmp_gt_f32_e32 vcc, s5, v196
	v_cmp_gt_f32_e64 s[38:39], s5, v197
	s_nop 1
	v_cndmask_b32_e64 v107, 0, 32, vcc
	v_cndmask_b32_e64 v233, 0, 32, s[38:39]
	v_ldexp_f32 v196, v196, v107
	v_ldexp_f32 v197, v197, v233
	v_log_f32_e32 v196, v196
	v_log_f32_e32 v197, v197
	v_cndmask_b32_e32 v107, 0, v223, vcc
	v_cndmask_b32_e64 v233, 0, v223, s[38:39]
	v_mul_f32_e32 v121, 0x3f317217, v196
	v_mul_f32_e32 v205, 0x3f317217, v197
	v_fma_f32 v121, v196, s75, -v121
	v_fma_f32 v205, v197, s75, -v205
	v_fmac_f32_e32 v121, 0x3377d1cf, v196
	v_fmac_f32_e32 v205, 0x3377d1cf, v197
	v_fmac_f32_e32 v121, 0x3f317217, v196
	v_fmac_f32_e32 v205, 0x3f317217, v197
	v_cmp_lt_f32_e64 vcc, |v196|, s33
	v_cmp_lt_f32_e64 s[38:39], |v197|, s33
	s_nop 1
	v_cndmask_b32_e32 v196, v196, v121, vcc
	v_cndmask_b32_e64 v197, v197, v205, s[38:39]
	v_sub_f32_e32 v196, v196, v107
	v_sub_f32_e32 v197, v197, v233
	v_sub_f32_e32 v196, v85, v196
	v_sub_f32_e32 v197, v191, v197
	v_mul_f32_e32 v196, 0x3d800000, v196
	v_mul_f32_e32 v197, 0x3d800000, v197
	ds_write_b32 v84, v196 offset:16
	ds_write_b32 v84, v197 offset:20
	v_min_f32_e32 v85, 0, v198
	v_min_f32_e32 v191, 0, v199
	v_mul_f32_e64 v198, |v198|, s36
	v_mul_f32_e64 v199, |v199|, s36
	v_exp_f32_e32 v198, v198
	v_exp_f32_e32 v199, v199
	s_nop 0
	v_add_f32_e32 v198, 1.0, v198
	v_add_f32_e32 v199, 1.0, v199
	v_cmp_gt_f32_e32 vcc, s5, v198
	v_cmp_gt_f32_e64 s[38:39], s5, v199
	s_nop 1
	v_cndmask_b32_e64 v107, 0, 32, vcc
	v_cndmask_b32_e64 v233, 0, 32, s[38:39]
	v_ldexp_f32 v198, v198, v107
	v_ldexp_f32 v199, v199, v233
	v_log_f32_e32 v198, v198
	v_log_f32_e32 v199, v199
	v_cndmask_b32_e32 v107, 0, v223, vcc
	v_cndmask_b32_e64 v233, 0, v223, s[38:39]
	v_mul_f32_e32 v121, 0x3f317217, v198
	v_mul_f32_e32 v205, 0x3f317217, v199
	v_fma_f32 v121, v198, s75, -v121
	v_fma_f32 v205, v199, s75, -v205
	v_fmac_f32_e32 v121, 0x3377d1cf, v198
	v_fmac_f32_e32 v205, 0x3377d1cf, v199
	v_fmac_f32_e32 v121, 0x3f317217, v198
	v_fmac_f32_e32 v205, 0x3f317217, v199
	v_cmp_lt_f32_e64 vcc, |v198|, s33
	v_cmp_lt_f32_e64 s[38:39], |v199|, s33
	s_nop 1
	v_cndmask_b32_e32 v198, v198, v121, vcc
	v_cndmask_b32_e64 v199, v199, v205, s[38:39]
	v_sub_f32_e32 v198, v198, v107
	v_sub_f32_e32 v199, v199, v233
	v_sub_f32_e32 v198, v85, v198
	v_sub_f32_e32 v199, v191, v199
	v_mul_f32_e32 v198, 0x3d800000, v198
	v_mul_f32_e32 v199, 0x3d800000, v199
	ds_write_b32 v84, v198 offset:24
	ds_write_b32 v84, v199 offset:28
	ds_read_b128 v[196:199], v83 offset:3104
	ds_read_b128 v[234:237], v83 offset:32
	ds_read_b128 v[238:241], v83 offset:224
	ds_read_b128 v[242:245], v83 offset:416
	ds_read_b128 v[246:249], v83 offset:608
	ds_read_b128 v[250:253], v83 offset:800
	ds_read_b128 v[192:195], v83 offset:992
	ds_read_b128 v[200:203], v83 offset:1184
	ds_read_b128 v[86:89], v83 offset:1376
	s_waitcnt lgkmcnt(4)
	v_fmac_f32_e32 v196, v234, v77
	v_fmac_f32_e32 v197, v235, v77
	v_fmac_f32_e32 v198, v236, v77
	v_fmac_f32_e32 v199, v237, v77
	v_fmac_f32_e32 v196, v238, v78
	v_fmac_f32_e32 v197, v239, v78
	v_fmac_f32_e32 v198, v240, v78
	v_fmac_f32_e32 v199, v241, v78
	v_fmac_f32_e32 v196, v242, v79
	v_fmac_f32_e32 v197, v243, v79
	v_fmac_f32_e32 v198, v244, v79
	v_fmac_f32_e32 v199, v245, v79
	v_fmac_f32_e32 v196, v246, v80
	v_fmac_f32_e32 v197, v247, v80
	v_fmac_f32_e32 v198, v248, v80
	v_fmac_f32_e32 v199, v249, v80
	ds_read_b128 v[234:237], v83 offset:1568
	ds_read_b128 v[238:241], v83 offset:1760
	ds_read_b128 v[242:245], v83 offset:1952
	ds_read_b128 v[246:249], v83 offset:2144
	s_waitcnt lgkmcnt(4)
	v_fmac_f32_e32 v196, v250, v81
	v_fmac_f32_e32 v197, v251, v81
	v_fmac_f32_e32 v198, v252, v81
	v_fmac_f32_e32 v199, v253, v81
	v_fmac_f32_e32 v196, v192, v82
	v_fmac_f32_e32 v197, v193, v82
	v_fmac_f32_e32 v198, v194, v82
	v_fmac_f32_e32 v199, v195, v82
	v_pk_mul_f32 v[90:91], v[200:201], v[2:3] op_sel_hi:[1,0]
	v_pk_mul_f32 v[204:205], v[202:203], v[2:3] op_sel_hi:[1,0]
	v_add_f32_e32 v196, v196, v90
	v_add_f32_e32 v197, v197, v91
	v_add_f32_e32 v198, v198, v204
	v_add_f32_e32 v199, v199, v205
	v_pk_mul_f32 v[90:91], v[86:87], v[2:3] op_sel:[0,1] op_sel_hi:[1,1]
	v_pk_mul_f32 v[204:205], v[88:89], v[2:3] op_sel:[0,1] op_sel_hi:[1,1]
	v_add_f32_e32 v196, v196, v90
	v_add_f32_e32 v197, v197, v91
	v_add_f32_e32 v198, v198, v204
	v_add_f32_e32 v199, v199, v205
	ds_read_b128 v[250:253], v83 offset:2336
	ds_read_b128 v[192:195], v83 offset:2528
	ds_read_b128 v[200:203], v83 offset:2720
	ds_read_b128 v[86:89], v83 offset:2912
	s_waitcnt lgkmcnt(4)
	v_pk_mul_f32 v[90:91], v[234:235], v[68:69] op_sel_hi:[1,0]
	v_pk_mul_f32 v[204:205], v[236:237], v[68:69] op_sel_hi:[1,0]
	v_add_f32_e32 v196, v196, v90
	v_add_f32_e32 v197, v197, v91
	v_add_f32_e32 v198, v198, v204
	v_add_f32_e32 v199, v199, v205
	v_pk_mul_f32 v[90:91], v[238:239], v[68:69] op_sel:[0,1] op_sel_hi:[1,1]
	v_pk_mul_f32 v[204:205], v[240:241], v[68:69] op_sel:[0,1] op_sel_hi:[1,1]
	v_add_f32_e32 v196, v196, v90
	v_add_f32_e32 v197, v197, v91
	v_add_f32_e32 v198, v198, v204
	v_add_f32_e32 v199, v199, v205
	v_pk_mul_f32 v[90:91], v[242:243], v[70:71] op_sel_hi:[1,0]
	v_pk_mul_f32 v[204:205], v[244:245], v[70:71] op_sel_hi:[1,0]
	v_add_f32_e32 v196, v196, v90
	v_add_f32_e32 v197, v197, v91
	v_add_f32_e32 v198, v198, v204
	v_add_f32_e32 v199, v199, v205
	v_pk_mul_f32 v[90:91], v[246:247], v[70:71] op_sel:[0,1] op_sel_hi:[1,1]
	v_pk_mul_f32 v[204:205], v[248:249], v[70:71] op_sel:[0,1] op_sel_hi:[1,1]
	v_add_f32_e32 v196, v196, v90
	v_add_f32_e32 v197, v197, v91
	v_add_f32_e32 v198, v198, v204
	v_add_f32_e32 v199, v199, v205
	s_waitcnt lgkmcnt(0)
	v_pk_mul_f32 v[90:91], v[250:251], v[72:73] op_sel_hi:[1,0]
	v_pk_mul_f32 v[204:205], v[252:253], v[72:73] op_sel_hi:[1,0]
	v_add_f32_e32 v196, v196, v90
	v_add_f32_e32 v197, v197, v91
	v_add_f32_e32 v198, v198, v204
	v_add_f32_e32 v199, v199, v205
	v_pk_mul_f32 v[90:91], v[192:193], v[72:73] op_sel:[0,1] op_sel_hi:[1,1]
	v_pk_mul_f32 v[204:205], v[194:195], v[72:73] op_sel:[0,1] op_sel_hi:[1,1]
	v_add_f32_e32 v196, v196, v90
	v_add_f32_e32 v197, v197, v91
	v_add_f32_e32 v198, v198, v204
	v_add_f32_e32 v199, v199, v205
	v_pk_mul_f32 v[90:91], v[200:201], v[74:75] op_sel_hi:[1,0]
	v_pk_mul_f32 v[204:205], v[202:203], v[74:75] op_sel_hi:[1,0]
	v_add_f32_e32 v196, v196, v90
	v_add_f32_e32 v197, v197, v91
	v_add_f32_e32 v198, v198, v204
	v_add_f32_e32 v199, v199, v205
	v_pk_mul_f32 v[90:91], v[86:87], v[74:75] op_sel:[0,1] op_sel_hi:[1,1]
	v_pk_mul_f32 v[204:205], v[88:89], v[74:75] op_sel:[0,1] op_sel_hi:[1,1]
	v_add_f32_e32 v196, v196, v90
	v_add_f32_e32 v197, v197, v91
	v_add_f32_e32 v198, v198, v204
	v_add_f32_e32 v199, v199, v205
	v_min_f32_e32 v85, 0, v196
	v_min_f32_e32 v191, 0, v197
	v_mul_f32_e64 v196, |v196|, s36
	v_mul_f32_e64 v197, |v197|, s36
	v_exp_f32_e32 v196, v196
	v_exp_f32_e32 v197, v197
	s_nop 0
	v_add_f32_e32 v196, 1.0, v196
	v_add_f32_e32 v197, 1.0, v197
	v_cmp_gt_f32_e32 vcc, s5, v196
	v_cmp_gt_f32_e64 s[38:39], s5, v197
	s_nop 1
	v_cndmask_b32_e64 v107, 0, 32, vcc
	v_cndmask_b32_e64 v233, 0, 32, s[38:39]
	v_ldexp_f32 v196, v196, v107
	v_ldexp_f32 v197, v197, v233
	v_log_f32_e32 v196, v196
	v_log_f32_e32 v197, v197
	v_cndmask_b32_e32 v107, 0, v223, vcc
	v_cndmask_b32_e64 v233, 0, v223, s[38:39]
	v_mul_f32_e32 v121, 0x3f317217, v196
	v_mul_f32_e32 v205, 0x3f317217, v197
	v_fma_f32 v121, v196, s75, -v121
	v_fma_f32 v205, v197, s75, -v205
	v_fmac_f32_e32 v121, 0x3377d1cf, v196
	v_fmac_f32_e32 v205, 0x3377d1cf, v197
	v_fmac_f32_e32 v121, 0x3f317217, v196
	v_fmac_f32_e32 v205, 0x3f317217, v197
	v_cmp_lt_f32_e64 vcc, |v196|, s33
	v_cmp_lt_f32_e64 s[38:39], |v197|, s33
	s_nop 1
	v_cndmask_b32_e32 v196, v196, v121, vcc
	v_cndmask_b32_e64 v197, v197, v205, s[38:39]
	v_sub_f32_e32 v196, v196, v107
	v_sub_f32_e32 v197, v197, v233
	v_sub_f32_e32 v196, v85, v196
	v_sub_f32_e32 v197, v191, v197
	v_mul_f32_e32 v196, 0x3d800000, v196
	v_mul_f32_e32 v197, 0x3d800000, v197
	ds_write_b32 v84, v196 offset:32
	ds_write_b32 v84, v197 offset:36
	v_min_f32_e32 v85, 0, v198
	v_min_f32_e32 v191, 0, v199
	v_mul_f32_e64 v198, |v198|, s36
	v_mul_f32_e64 v199, |v199|, s36
	v_exp_f32_e32 v198, v198
	v_exp_f32_e32 v199, v199
	s_nop 0
	v_add_f32_e32 v198, 1.0, v198
	v_add_f32_e32 v199, 1.0, v199
	v_cmp_gt_f32_e32 vcc, s5, v198
	v_cmp_gt_f32_e64 s[38:39], s5, v199
	s_nop 1
	v_cndmask_b32_e64 v107, 0, 32, vcc
	v_cndmask_b32_e64 v233, 0, 32, s[38:39]
	v_ldexp_f32 v198, v198, v107
	v_ldexp_f32 v199, v199, v233
	v_log_f32_e32 v198, v198
	v_log_f32_e32 v199, v199
	v_cndmask_b32_e32 v107, 0, v223, vcc
	v_cndmask_b32_e64 v233, 0, v223, s[38:39]
	v_mul_f32_e32 v121, 0x3f317217, v198
	v_mul_f32_e32 v205, 0x3f317217, v199
	v_fma_f32 v121, v198, s75, -v121
	v_fma_f32 v205, v199, s75, -v205
	v_fmac_f32_e32 v121, 0x3377d1cf, v198
	v_fmac_f32_e32 v205, 0x3377d1cf, v199
	v_fmac_f32_e32 v121, 0x3f317217, v198
	v_fmac_f32_e32 v205, 0x3f317217, v199
	v_cmp_lt_f32_e64 vcc, |v198|, s33
	v_cmp_lt_f32_e64 s[38:39], |v199|, s33
	s_nop 1
	v_cndmask_b32_e32 v198, v198, v121, vcc
	v_cndmask_b32_e64 v199, v199, v205, s[38:39]
	v_sub_f32_e32 v198, v198, v107
	v_sub_f32_e32 v199, v199, v233
	v_sub_f32_e32 v198, v85, v198
	v_sub_f32_e32 v199, v191, v199
	v_mul_f32_e32 v198, 0x3d800000, v198
	v_mul_f32_e32 v199, 0x3d800000, v199
	ds_write_b32 v84, v198 offset:40
	ds_write_b32 v84, v199 offset:44
	s_waitcnt lgkmcnt(0)
	s_barrier
	s_and_saveexec_b64 s[68:69], s[48:49]
	s_cbranch_execz .LBB0_598
	v_mov_b32_e32 v2, 0
	s_mov_b32 s38, 0

.LBB0_610:
	s_cmp_eq_u32 s92, 0x100
	s_cbranch_scc0 .Lprep_noxor
	s_xor_b32 s1, s1, 0x80
	v_xor_b32_e32 v128, 64, v128
	s_nop 0
	v_mul_hi_i32 v131, v128, s7
